# one static s_setprio 1 for waves 4-7 through the attention phase (reset before the phase-end barrier)
# baseline (speedup 1.0000x reference)
; #define KA_BEGIN() kargp_t KA = (kargp_t)__builtin_amdgcn_kernarg_segment_ptr(); asm volatile("" : "+s"(KA)); unsigned char* const ws = (unsigned char*)(GAS unsigned char*)KA[29]; float* const out = (float*)(GAS float*)KA[28]; (void)ws; (void)out
; #define TIDS() int tid = threadIdx.x; asm volatile("" : "+v"(tid)); const int lane = tid & 63, wave = __builtin_amdgcn_readfirstlane(tid >> 6); const int gw = bid * NWAVES + wave, NGW = G * NWAVES; (void)lane; (void)gw; (void)NGW
; __global__ void __launch_bounds__(NTHR, 2) fwd_kernel(Args args) {
;     ...
;     if (PH(3)) { KA_BEGIN(); TIDS();
;         unsigned* ctl = (unsigned*)(ws + WS_CTL);
;     ...
;         if (bid < 4) { const float *PE = (const float*)(ws + WS_PE), *LE = (const float*)(ws + WS_LE); float* HIN = (float*)(ws + WS_HIN); const int chn = bid * NTHR + tid; float H = 0.f;
;             for (int c0 = 0; c0 < NCH; c0 += 8) { float p[8], l[8];
.LBB0_1270:
	s_or_b64 exec, exec, s[6:7]
	s_mov_b64 s[20:21], s[96:97]
	s_waitcnt lgkmcnt(0)
	s_barrier
	v_readfirstlane_b32 s98, v0
	s_nop 3
	s_lshr_b32 s98, s98, 6
	s_cmp_ge_u32 s98, 4
	s_cbranch_scc0 .Lp3prio_done
	s_setprio 1
.Lp3prio_done:
	s_load_dwordx2 s[22:23], s[20:21], 0xe8
	s_cmp_lt_i32 s2, 4
	v_mov_b32_e32 v69, v0
	s_cbranch_scc0 .LBB0_1301
	v_lshl_add_u32 v2, s2, 9, v69
	v_ashrrev_i32_e32 v3, 31, v2
	s_waitcnt lgkmcnt(0)
	v_lshl_add_u64 v[2:3], v[2:3], 2, s[22:23]
	s_mov_b64 s[0:1], 0xa00000
	v_lshl_add_u64 v[2:3], v[2:3], 0, s[0:1]
	v_mov_b32_e32 v4, 0
	s_mov_b32 s0, 7
	s_mov_b64 s[6:7], 0x10000
	s_branch .LBB0_1273

; __device__ __forceinline__ unsigned xb_ld(unsigned* p)              { return __hip_atomic_load(p, __ATOMIC_RELAXED, __HIP_MEMORY_SCOPE_AGENT); }
; __device__ __forceinline__ void xcd_barrier_complete(unsigned* bar, unsigned x, unsigned& nloc, unsigned& nx) {
;     const unsigned G = gridDim.x * gridDim.y * gridDim.z;
;     unsigned sum, cnt, mine, sp = 0u;
;     for (;;) {
;         sum = 0u; cnt = 0u; mine = 0u;
; #pragma unroll
;         for (unsigned j = 0; j < 16; ++j) { const unsigned c = xb_ld(&bar[XB_XCNT(j)]); sum += c; cnt += (c > 0u) ? 1u : 0u; mine = (j == x) ? c : mine; }
; __device__ __forceinline__ void xcd_barrier(const XcdBarrier& b) {
;     asm volatile("s_waitcnt vmcnt(0)" ::: "memory");
;     __syncthreads();
;     if (threadIdx.x == 0) {
;         unsigned* bar = b.bar;
;         __builtin_amdgcn_s_waitcnt(0);
;         unsigned nloc = b.st[0], nx = b.st[1];
;         if (nloc == 0u) { xcd_barrier_complete(bar, b.x, nloc, nx); b.st[0] = nloc; b.st[1] = nx; }
.LBB0_2236:
	s_waitcnt vmcnt(0)
	s_setprio 0
	s_barrier
	s_mov_b64 s[6:7], exec
	v_readlane_b32 s0, v255, 7
	v_readlane_b32 s1, v255, 8
	s_and_b64 s[0:1], s[6:7], s[0:1]
	s_mov_b64 exec, s[0:1]
	s_cbranch_execz .LBB0_2288
	s_add_i32 s0, 0, 0x24020
	v_mov_b32_e32 v1, s0
	s_waitcnt vmcnt(0) expcnt(0) lgkmcnt(0)
	ds_read_b32 v4, v1
	s_add_i32 s0, 0, 0x24024
	v_mov_b32_e32 v1, s0
	ds_read_b32 v2, v1
	s_waitcnt lgkmcnt(1)
	v_cmp_ne_u32_e32 vcc, 0, v4
	s_cbranch_vccnz .LBB0_2252
	v_readlane_b32 s8, v255, 2
	v_readlane_b32 s9, v255, 3
	v_readlane_b32 s42, v255, 0
	s_load_dwordx2 s[0:1], s[8:9], 0x4
	v_readlane_b32 s43, v255, 1
	s_add_u32 s8, s42, 0x4200
	s_addc_u32 s9, s43, 0
	s_add_u32 s10, s42, 0x4400
	s_addc_u32 s11, s43, 0
	s_add_u32 s12, s42, 0x4500
	s_addc_u32 s13, s43, 0
	s_add_u32 s14, s42, 0x4600
	s_addc_u32 s15, s43, 0
	s_add_u32 s16, s42, 0x4700
	s_addc_u32 s17, s43, 0
	s_add_u32 s18, s42, 0x4800
	s_addc_u32 s19, s43, 0
	s_add_u32 s20, s42, 0x4900
	s_addc_u32 s21, s43, 0
	s_add_u32 s22, s42, 0x4a00
	s_addc_u32 s23, s43, 0
	s_add_u32 s24, s42, 0x4b00
	s_addc_u32 s25, s43, 0
	s_add_u32 s26, s42, 0x4c00
	s_addc_u32 s27, s43, 0
	s_add_u32 s28, s42, 0x4d00
	s_addc_u32 s29, s43, 0
	s_add_u32 s30, s42, 0x4e00
	s_addc_u32 s31, s43, 0
	s_add_u32 s34, s42, 0x4f00
	s_addc_u32 s35, s43, 0
	s_add_u32 s36, s42, 0x5000
	s_addc_u32 s37, s43, 0
	s_add_u32 s38, s42, 0x5100
	s_addc_u32 s39, s43, 0
	s_add_u32 s40, s42, 0x5200
	s_addc_u32 s41, s43, 0
	s_waitcnt lgkmcnt(0)
	s_mul_i32 s0, s0, s33
	s_add_u32 s42, s42, 0x5300
	s_mul_i32 s0, s0, s1
	s_addc_u32 s43, s43, 0
	s_mov_b32 s1, 1
	v_mov_b32_e32 v18, 0
	s_branch .LBB0_2240
